# saddr-form LDS-DMA also in the P4 and P6 K-loops
# baseline (speedup 1.0000x reference)
; #define PG8_STAGE(bufoff, gbase, voff) do { _Pragma("unroll") for (int _i = 0; _i < 2; ++_i) \
;         __builtin_amdgcn_global_load_lds((const unsigned*)((const char*)(gbase) + (voff)[_i]), (PG8_LAS unsigned*)(lds + (bufoff) + ldsw + _i * 8192), 16, 0, 0); } while (0)
; #define PG8_LDA(dst, b, h) do { _Pragma("unroll") for (int m = 0; m < 4; ++m) _Pragma("unroll") for (int k = 0; k < 2; ++k) dst[m][k] = *(const PG8_LAS bf16x8*)(lds + PG8_SA(b, h) + aoff + m * 2048 + k * 1024); } while (0)
; #define PG8_LDB(dst, b, h) do { _Pragma("unroll") for (int n = 0; n < 2; ++n) _Pragma("unroll") for (int k = 0; k < 2; ++k) dst[n][k] = *(const PG8_LAS bf16x8*)(lds + PG8_SB(b, h) + boff + n * 2048 + k * 1024); } while (0)
; #define PG8_MMA(ai, bj, At, Bt) do { __builtin_amdgcn_s_setprio(1); _Pragma("unroll") for (int m = 0; m < 4; ++m) _Pragma("unroll") for (int n = 0; n < 2; ++n) _Pragma("unroll") for (int k = 0; k < 2; ++k) \
;         acc[ai][bj][m][n] = __builtin_amdgcn_mfma_f32_16x16x32_bf16(Bt[n][k], At[m][k], acc[ai][bj][m][n], 0, 0, 0); __builtin_amdgcn_s_setprio(0); } while (0)
; #define PG8_WAIT_V(n) asm volatile("s_waitcnt vmcnt(" #n ")" ::: "memory")
; #define PG8_WAIT_L(n) asm volatile("s_waitcnt lgkmcnt(" #n ")" ::: "memory")
; #define PG8_BAR __builtin_amdgcn_s_barrier()
; #define PG8_SCHED __builtin_amdgcn_sched_barrier(0)
; template <class Epi, class Sched, bool ALIGN_EPI = false, bool SP2 = false, bool SPLITK = false>
; __device__ __forceinline__ void gemm_phase(PG8_LAS unsigned char* lds, const Gemm g, const Sched& S, const Epi& E) {
;     ...
;             PG8_LDB(B0, 0, 0); PG8_LDB(B1, 0, 1); PG8_SCHED; PG8_LDA(At, 0, 0); PG8_STAGE(PG8_SA(1, 1), a1 + hstep, voffA);
;             PG8_WAIT_V(8); PG8_WAIT_L(0); PG8_BAR; PG8_MMA(0, 0, At, B0); PG8_MMA(0, 1, At, B1); PG8_BAR; PG8_SCHED;
;             PG8_LDA(At, 0, 1); PG8_STAGE(PG8_SB(0, 0), b2, voffB); PG8_STAGE(PG8_SB(0, 1), b2 + hstep, voffB); PG8_STAGE(PG8_SA(0, 0), a2, voffA);
;             PG8_WAIT_V(8); PG8_WAIT_L(0); PG8_BAR; PG8_MMA(1, 0, At, B0); PG8_MMA(1, 1, At, B1); PG8_BAR; PG8_SCHED;
.LBB0_510:
	s_add_u32 s46, s52, 0xfffc0080
	s_addc_u32 s47, s53, -1
	s_add_i32 s59, 0, 0x10000
	s_cmp_eq_u32 s58, 12
	s_cselect_b32 s49, s12, s47
	s_cselect_b32 s48, s19, s46
	s_cselect_b32 s47, s21, s45
	s_cselect_b32 s46, s35, s43
	s_add_i32 s68, 0, 0x14000
	v_add_u32_e32 v118, s59, v224
	v_add_u32_e32 v150, s68, v224
	ds_read_b128 v[82:85], v118
	ds_read_b128 v[94:97], v118 offset:1024
	ds_read_b128 v[106:109], v118 offset:2048
	ds_read_b128 v[118:121], v118 offset:3072
	ds_read_b128 v[130:133], v150
	ds_read_b128 v[142:145], v150 offset:1024
	ds_read_b128 v[146:149], v150 offset:2048
	ds_read_b128 v[150:153], v150 offset:3072
	s_add_i32 m0, s25, 0xc000
	ds_read_b128 v[162:165], v225
	ds_read_b128 v[166:169], v225 offset:1024
	ds_read_b128 v[170:173], v225 offset:2048
	ds_read_b128 v[174:177], v225 offset:3072
	ds_read_b128 v[178:181], v225 offset:4096
	ds_read_b128 v[182:185], v225 offset:5120
	ds_read_b128 v[186:189], v225 offset:6144
	ds_read_b128 v[190:193], v225 offset:7168
	global_load_lds_dwordx4 v200, s[52:53]
	s_add_i32 m0, s25, 0xe000
	s_nop 0
	global_load_lds_dwordx4 v202, s[52:53]
	s_waitcnt vmcnt(8)
	s_waitcnt lgkmcnt(0)
	s_barrier
	s_setprio 1
	s_waitcnt lgkmcnt(0)
	v_mfma_f32_16x16x32_bf16 v[158:161], v[82:85], v[162:165], v[158:161]
	v_mfma_f32_16x16x32_bf16 v[154:157], v[106:109], v[162:165], v[154:157]
	v_mfma_f32_16x16x32_bf16 v[126:129], v[82:85], v[170:173], v[126:129]
	v_mfma_f32_16x16x32_bf16 v[122:125], v[106:109], v[170:173], v[122:125]
	v_mfma_f32_16x16x32_bf16 v[102:105], v[82:85], v[178:181], v[102:105]
	v_mfma_f32_16x16x32_bf16 v[98:101], v[106:109], v[178:181], v[98:101]
	v_mfma_f32_16x16x32_bf16 v[78:81], v[82:85], v[186:189], v[78:81]
	v_mfma_f32_16x16x32_bf16 v[74:77], v[106:109], v[186:189], v[74:77]
	v_mfma_f32_16x16x32_bf16 v[158:161], v[94:97], v[166:169], v[158:161]
	v_mfma_f32_16x16x32_bf16 v[154:157], v[118:121], v[166:169], v[154:157]
	v_mfma_f32_16x16x32_bf16 v[126:129], v[94:97], v[174:177], v[126:129]
	v_mfma_f32_16x16x32_bf16 v[122:125], v[118:121], v[174:177], v[122:125]
	v_mfma_f32_16x16x32_bf16 v[102:105], v[94:97], v[182:185], v[102:105]
	v_mfma_f32_16x16x32_bf16 v[98:101], v[118:121], v[182:185], v[98:101]
	v_mfma_f32_16x16x32_bf16 v[78:81], v[94:97], v[190:193], v[78:81]
	v_mfma_f32_16x16x32_bf16 v[74:77], v[118:121], v[190:193], v[74:77]
	s_setprio 0
	s_setprio 1
	v_mfma_f32_16x16x32_bf16 v[138:141], v[130:133], v[162:165], v[138:141]
	v_mfma_f32_16x16x32_bf16 v[134:137], v[146:149], v[162:165], v[134:137]
	v_mfma_f32_16x16x32_bf16 v[114:117], v[130:133], v[170:173], v[114:117]
	v_mfma_f32_16x16x32_bf16 v[110:113], v[146:149], v[170:173], v[110:113]
	v_mfma_f32_16x16x32_bf16 v[90:93], v[130:133], v[178:181], v[90:93]
	v_mfma_f32_16x16x32_bf16 v[86:89], v[146:149], v[178:181], v[86:89]
	v_mfma_f32_16x16x32_bf16 v[70:73], v[130:133], v[186:189], v[70:73]
	v_mfma_f32_16x16x32_bf16 v[66:69], v[146:149], v[186:189], v[66:69]
	v_mfma_f32_16x16x32_bf16 v[138:141], v[142:145], v[166:169], v[138:141]
	v_mfma_f32_16x16x32_bf16 v[134:137], v[150:153], v[166:169], v[134:137]
	v_mfma_f32_16x16x32_bf16 v[114:117], v[142:145], v[174:177], v[114:117]
	v_mfma_f32_16x16x32_bf16 v[110:113], v[150:153], v[174:177], v[110:113]
	v_mfma_f32_16x16x32_bf16 v[90:93], v[142:145], v[182:185], v[90:93]
	v_mfma_f32_16x16x32_bf16 v[86:89], v[150:153], v[182:185], v[86:89]
	v_mfma_f32_16x16x32_bf16 v[70:73], v[142:145], v[190:193], v[70:73]
	v_mfma_f32_16x16x32_bf16 v[66:69], v[150:153], v[190:193], v[66:69]
	s_setprio 0
	s_barrier
	s_add_i32 s59, s59, s24
	s_mov_b32 m0, s59
	ds_read_b128 v[162:165], v225 offset:16384
	ds_read_b128 v[166:169], v225 offset:17408
	ds_read_b128 v[170:173], v225 offset:18432
	ds_read_b128 v[174:177], v225 offset:19456
	ds_read_b128 v[178:181], v225 offset:20480
	ds_read_b128 v[182:185], v225 offset:21504
	ds_read_b128 v[186:189], v225 offset:22528
	ds_read_b128 v[190:193], v225 offset:23552
	global_load_lds_dwordx4 v0, s[46:47]
	s_add_i32 m0, s59, 0x2000
	s_add_u32 s64, s46, 0x40000
	s_addc_u32 s65, s47, 0
	s_add_i32 s59, s68, s24
	global_load_lds_dwordx4 v198, s[46:47]
	s_mov_b32 m0, s59
	s_nop 0
	global_load_lds_dwordx4 v0, s[64:65]
	s_add_i32 m0, s59, 0x2000
	s_nop 0
	global_load_lds_dwordx4 v198, s[64:65]
	s_mov_b32 m0, s25
	s_nop 0
	global_load_lds_dwordx4 v194, s[48:49]
	s_mov_b32 m0, s33
	s_nop 0
	global_load_lds_dwordx4 v196, s[48:49]
	s_waitcnt vmcnt(8)
	s_waitcnt lgkmcnt(0)
	s_barrier
	s_setprio 1
	s_waitcnt lgkmcnt(0)
	v_mfma_f32_16x16x32_bf16 v[62:65], v[82:85], v[162:165], v[62:65]
	v_mfma_f32_16x16x32_bf16 v[58:61], v[106:109], v[162:165], v[58:61]
	v_mfma_f32_16x16x32_bf16 v[46:49], v[82:85], v[170:173], v[46:49]
	v_mfma_f32_16x16x32_bf16 v[42:45], v[106:109], v[170:173], v[42:45]
	v_mfma_f32_16x16x32_bf16 v[30:33], v[82:85], v[178:181], v[30:33]
	v_mfma_f32_16x16x32_bf16 v[26:29], v[106:109], v[178:181], v[26:29]
	v_mfma_f32_16x16x32_bf16 v[14:17], v[82:85], v[186:189], v[14:17]
	v_mfma_f32_16x16x32_bf16 v[10:13], v[106:109], v[186:189], v[10:13]
	v_mfma_f32_16x16x32_bf16 v[62:65], v[94:97], v[166:169], v[62:65]
	v_mfma_f32_16x16x32_bf16 v[58:61], v[118:121], v[166:169], v[58:61]
	v_mfma_f32_16x16x32_bf16 v[46:49], v[94:97], v[174:177], v[46:49]
	v_mfma_f32_16x16x32_bf16 v[42:45], v[118:121], v[174:177], v[42:45]
	v_mfma_f32_16x16x32_bf16 v[30:33], v[94:97], v[182:185], v[30:33]
	v_mfma_f32_16x16x32_bf16 v[26:29], v[118:121], v[182:185], v[26:29]
	v_mfma_f32_16x16x32_bf16 v[14:17], v[94:97], v[190:193], v[14:17]
	v_mfma_f32_16x16x32_bf16 v[10:13], v[118:121], v[190:193], v[10:13]
	s_setprio 0
	s_setprio 1
	v_mfma_f32_16x16x32_bf16 v[54:57], v[130:133], v[162:165], v[54:57]
	v_mfma_f32_16x16x32_bf16 v[50:53], v[146:149], v[162:165], v[50:53]
	v_mfma_f32_16x16x32_bf16 v[38:41], v[130:133], v[170:173], v[38:41]
	v_mfma_f32_16x16x32_bf16 v[34:37], v[146:149], v[170:173], v[34:37]
	v_mfma_f32_16x16x32_bf16 v[22:25], v[130:133], v[178:181], v[22:25]
	v_mfma_f32_16x16x32_bf16 v[18:21], v[146:149], v[178:181], v[18:21]
	v_mfma_f32_16x16x32_bf16 v[6:9], v[130:133], v[186:189], v[6:9]
	v_mfma_f32_16x16x32_bf16 v[2:5], v[146:149], v[186:189], v[2:5]
	v_mfma_f32_16x16x32_bf16 v[54:57], v[142:145], v[166:169], v[54:57]
	v_mfma_f32_16x16x32_bf16 v[50:53], v[150:153], v[166:169], v[50:53]
	v_mfma_f32_16x16x32_bf16 v[38:41], v[142:145], v[174:177], v[38:41]
	v_mfma_f32_16x16x32_bf16 v[34:37], v[150:153], v[174:177], v[34:37]
	v_mfma_f32_16x16x32_bf16 v[22:25], v[142:145], v[182:185], v[22:25]
	v_mfma_f32_16x16x32_bf16 v[18:21], v[150:153], v[182:185], v[18:21]
	v_mfma_f32_16x16x32_bf16 v[6:9], v[142:145], v[190:193], v[6:9]
	v_mfma_f32_16x16x32_bf16 v[2:5], v[150:153], v[190:193], v[2:5]
	s_setprio 0
	s_barrier
; #define PG8_STAGE(bufoff, gbase, voff) do { _Pragma("unroll") for (int _i = 0; _i < 2; ++_i) \
;         __builtin_amdgcn_global_load_lds((const unsigned*)((const char*)(gbase) + (voff)[_i]), (PG8_LAS unsigned*)(lds + (bufoff) + ldsw + _i * 8192), 16, 0, 0); } while (0)
; #define PG8_LDA(dst, b, h) do { _Pragma("unroll") for (int m = 0; m < 4; ++m) _Pragma("unroll") for (int k = 0; k < 2; ++k) dst[m][k] = *(const PG8_LAS bf16x8*)(lds + PG8_SA(b, h) + aoff + m * 2048 + k * 1024); } while (0)
; #define PG8_LDB(dst, b, h) do { _Pragma("unroll") for (int n = 0; n < 2; ++n) _Pragma("unroll") for (int k = 0; k < 2; ++k) dst[n][k] = *(const PG8_LAS bf16x8*)(lds + PG8_SB(b, h) + boff + n * 2048 + k * 1024); } while (0)
; #define PG8_MMA(ai, bj, At, Bt) do { __builtin_amdgcn_s_setprio(1); _Pragma("unroll") for (int m = 0; m < 4; ++m) _Pragma("unroll") for (int n = 0; n < 2; ++n) _Pragma("unroll") for (int k = 0; k < 2; ++k) \
;         acc[ai][bj][m][n] = __builtin_amdgcn_mfma_f32_16x16x32_bf16(Bt[n][k], At[m][k], acc[ai][bj][m][n], 0, 0, 0); __builtin_amdgcn_s_setprio(0); } while (0)
; #define PG8_WAIT_V(n) asm volatile("s_waitcnt vmcnt(" #n ")" ::: "memory")
; #define PG8_WAIT_L(n) asm volatile("s_waitcnt lgkmcnt(" #n ")" ::: "memory")
; #define PG8_BAR __builtin_amdgcn_s_barrier()
; #define PG8_SCHED __builtin_amdgcn_sched_barrier(0)
; template <class Epi, class Sched, bool ALIGN_EPI = false, bool SP2 = false, bool SPLITK = false>
; __device__ __forceinline__ void gemm_phase(PG8_LAS unsigned char* lds, const Gemm g, const Sched& S, const Epi& E) {
;     ...
;             PG8_LDB(B0, 1, 0); PG8_LDB(B1, 1, 1); PG8_SCHED; PG8_LDA(At, 1, 0); PG8_STAGE(PG8_SA(0, 1), a2 + hstep, voffA);
;             PG8_WAIT_V(8); PG8_WAIT_L(0); PG8_BAR; PG8_MMA(0, 0, At, B0); PG8_MMA(0, 1, At, B1); PG8_BAR; PG8_SCHED;
;             PG8_LDA(At, 1, 1); PG8_STAGE(PG8_SB(1, 0), b3, voffB); PG8_STAGE(PG8_SB(1, 1), b3 + hstep, voffB); PG8_STAGE(PG8_SA(1, 0), a3, voffA);
;             PG8_WAIT_V(8); PG8_WAIT_L(0); PG8_BAR; PG8_MMA(1, 0, At, B0); PG8_MMA(1, 1, At, B1); PG8_BAR; PG8_SCHED;
	s_add_i32 s59, 0, 0x18000
	s_add_i32 s64, 0, 0x1c000
	v_add_u32_e32 v118, s59, v224
	v_add_u32_e32 v150, s64, v224
	ds_read_b128 v[82:85], v118
	ds_read_b128 v[94:97], v118 offset:1024
	ds_read_b128 v[106:109], v118 offset:2048
	ds_read_b128 v[118:121], v118 offset:3072
	ds_read_b128 v[130:133], v150
	ds_read_b128 v[142:145], v150 offset:1024
	ds_read_b128 v[146:149], v150 offset:2048
	ds_read_b128 v[150:153], v150 offset:3072
	s_add_u32 vcc_lo, s48, 0x80
	s_addc_u32 vcc_hi, s49, 0
	s_add_u32 s48, s48, 0x40000
	s_addc_u32 s49, s49, 0
	s_mov_b32 m0, s50
	ds_read_b128 v[162:165], v225 offset:32768
	ds_read_b128 v[166:169], v225 offset:33792
	ds_read_b128 v[170:173], v225 offset:34816
	ds_read_b128 v[174:177], v225 offset:35840
	ds_read_b128 v[178:181], v225 offset:36864
	ds_read_b128 v[182:185], v225 offset:37888
	ds_read_b128 v[186:189], v225 offset:38912
	ds_read_b128 v[190:193], v225 offset:39936
	global_load_lds_dwordx4 v194, s[48:49]
	s_mov_b32 m0, s51
	s_nop 0
	global_load_lds_dwordx4 v196, s[48:49]
	s_waitcnt vmcnt(8)
	s_waitcnt lgkmcnt(0)
	s_barrier
	s_setprio 1
	s_waitcnt lgkmcnt(0)
	v_mfma_f32_16x16x32_bf16 v[158:161], v[82:85], v[162:165], v[158:161]
	v_mfma_f32_16x16x32_bf16 v[154:157], v[106:109], v[162:165], v[154:157]
	v_mfma_f32_16x16x32_bf16 v[126:129], v[82:85], v[170:173], v[126:129]
	v_mfma_f32_16x16x32_bf16 v[122:125], v[106:109], v[170:173], v[122:125]
	v_mfma_f32_16x16x32_bf16 v[102:105], v[82:85], v[178:181], v[102:105]
	v_mfma_f32_16x16x32_bf16 v[98:101], v[106:109], v[178:181], v[98:101]
	v_mfma_f32_16x16x32_bf16 v[78:81], v[82:85], v[186:189], v[78:81]
	v_mfma_f32_16x16x32_bf16 v[74:77], v[106:109], v[186:189], v[74:77]
	v_mfma_f32_16x16x32_bf16 v[158:161], v[94:97], v[166:169], v[158:161]
	v_mfma_f32_16x16x32_bf16 v[154:157], v[118:121], v[166:169], v[154:157]
	v_mfma_f32_16x16x32_bf16 v[126:129], v[94:97], v[174:177], v[126:129]
	v_mfma_f32_16x16x32_bf16 v[122:125], v[118:121], v[174:177], v[122:125]
	v_mfma_f32_16x16x32_bf16 v[102:105], v[94:97], v[182:185], v[102:105]
	v_mfma_f32_16x16x32_bf16 v[98:101], v[118:121], v[182:185], v[98:101]
	v_mfma_f32_16x16x32_bf16 v[78:81], v[94:97], v[190:193], v[78:81]
	v_mfma_f32_16x16x32_bf16 v[74:77], v[118:121], v[190:193], v[74:77]
	s_setprio 0
	s_setprio 1
	v_mfma_f32_16x16x32_bf16 v[138:141], v[130:133], v[162:165], v[138:141]
	v_mfma_f32_16x16x32_bf16 v[134:137], v[146:149], v[162:165], v[134:137]
	v_mfma_f32_16x16x32_bf16 v[114:117], v[130:133], v[170:173], v[114:117]
	v_mfma_f32_16x16x32_bf16 v[110:113], v[146:149], v[170:173], v[110:113]
	v_mfma_f32_16x16x32_bf16 v[90:93], v[130:133], v[178:181], v[90:93]
	v_mfma_f32_16x16x32_bf16 v[86:89], v[146:149], v[178:181], v[86:89]
	v_mfma_f32_16x16x32_bf16 v[70:73], v[130:133], v[186:189], v[70:73]
	v_mfma_f32_16x16x32_bf16 v[66:69], v[146:149], v[186:189], v[66:69]
	v_mfma_f32_16x16x32_bf16 v[138:141], v[142:145], v[166:169], v[138:141]
	v_mfma_f32_16x16x32_bf16 v[134:137], v[150:153], v[166:169], v[134:137]
	v_mfma_f32_16x16x32_bf16 v[114:117], v[142:145], v[174:177], v[114:117]
	v_mfma_f32_16x16x32_bf16 v[110:113], v[150:153], v[174:177], v[110:113]
	v_mfma_f32_16x16x32_bf16 v[90:93], v[142:145], v[182:185], v[90:93]
	v_mfma_f32_16x16x32_bf16 v[86:89], v[150:153], v[182:185], v[86:89]
	v_mfma_f32_16x16x32_bf16 v[70:73], v[142:145], v[190:193], v[70:73]
	v_mfma_f32_16x16x32_bf16 v[66:69], v[150:153], v[190:193], v[66:69]
	s_setprio 0
	s_barrier
	s_add_i32 s48, s59, s24
	s_add_u32 s46, s46, 0x80
	s_addc_u32 s47, s47, 0
	s_mov_b32 m0, s48
	ds_read_b128 v[162:165], v225 offset:49152
	ds_read_b128 v[166:169], v225 offset:50176
	ds_read_b128 v[170:173], v225 offset:51200
	ds_read_b128 v[174:177], v225 offset:52224
	ds_read_b128 v[178:181], v225 offset:53248
	ds_read_b128 v[182:185], v225 offset:54272
	ds_read_b128 v[186:189], v225 offset:55296
	ds_read_b128 v[190:193], v225 offset:56320
	global_load_lds_dwordx4 v0, s[46:47]
	s_add_i32 m0, s48, 0x2000
	s_add_i32 s48, s64, s24
	global_load_lds_dwordx4 v198, s[46:47]
	s_add_u32 s46, s46, 0x40000
	s_addc_u32 s47, s47, 0
	s_mov_b32 m0, s48
	s_nop 0
	global_load_lds_dwordx4 v0, s[46:47]
	s_add_i32 m0, s48, 0x2000
	s_nop 0
	global_load_lds_dwordx4 v198, s[46:47]
	s_mov_b32 m0, s54
	s_nop 0
	global_load_lds_dwordx4 v194, vcc
	s_mov_b32 m0, s55
	s_nop 0
	global_load_lds_dwordx4 v196, vcc
	s_waitcnt vmcnt(8)
	s_waitcnt lgkmcnt(0)
	s_barrier
	s_setprio 1
	s_waitcnt lgkmcnt(0)
	v_mfma_f32_16x16x32_bf16 v[62:65], v[82:85], v[162:165], v[62:65]
	v_mfma_f32_16x16x32_bf16 v[58:61], v[106:109], v[162:165], v[58:61]
	v_mfma_f32_16x16x32_bf16 v[46:49], v[82:85], v[170:173], v[46:49]
	v_mfma_f32_16x16x32_bf16 v[42:45], v[106:109], v[170:173], v[42:45]
	v_mfma_f32_16x16x32_bf16 v[30:33], v[82:85], v[178:181], v[30:33]
	v_mfma_f32_16x16x32_bf16 v[26:29], v[106:109], v[178:181], v[26:29]
	v_mfma_f32_16x16x32_bf16 v[14:17], v[82:85], v[186:189], v[14:17]
	v_mfma_f32_16x16x32_bf16 v[10:13], v[106:109], v[186:189], v[10:13]
	v_mfma_f32_16x16x32_bf16 v[62:65], v[94:97], v[166:169], v[62:65]
	v_mfma_f32_16x16x32_bf16 v[58:61], v[118:121], v[166:169], v[58:61]
	v_mfma_f32_16x16x32_bf16 v[46:49], v[94:97], v[174:177], v[46:49]
	v_mfma_f32_16x16x32_bf16 v[42:45], v[118:121], v[174:177], v[42:45]
	v_mfma_f32_16x16x32_bf16 v[30:33], v[94:97], v[182:185], v[30:33]
	v_mfma_f32_16x16x32_bf16 v[26:29], v[118:121], v[182:185], v[26:29]
	v_mfma_f32_16x16x32_bf16 v[14:17], v[94:97], v[190:193], v[14:17]
	v_mfma_f32_16x16x32_bf16 v[10:13], v[118:121], v[190:193], v[10:13]
	s_setprio 0
	s_setprio 1
	v_mfma_f32_16x16x32_bf16 v[54:57], v[130:133], v[162:165], v[54:57]
	v_mfma_f32_16x16x32_bf16 v[50:53], v[146:149], v[162:165], v[50:53]
	v_mfma_f32_16x16x32_bf16 v[38:41], v[130:133], v[170:173], v[38:41]
	v_mfma_f32_16x16x32_bf16 v[34:37], v[146:149], v[170:173], v[34:37]
	v_mfma_f32_16x16x32_bf16 v[22:25], v[130:133], v[178:181], v[22:25]
	v_mfma_f32_16x16x32_bf16 v[18:21], v[146:149], v[178:181], v[18:21]
	v_mfma_f32_16x16x32_bf16 v[6:9], v[130:133], v[186:189], v[6:9]
	v_mfma_f32_16x16x32_bf16 v[2:5], v[146:149], v[186:189], v[2:5]
	v_mfma_f32_16x16x32_bf16 v[54:57], v[142:145], v[166:169], v[54:57]
	v_mfma_f32_16x16x32_bf16 v[50:53], v[150:153], v[166:169], v[50:53]
	v_mfma_f32_16x16x32_bf16 v[38:41], v[142:145], v[174:177], v[38:41]
	v_mfma_f32_16x16x32_bf16 v[34:37], v[150:153], v[174:177], v[34:37]
	v_mfma_f32_16x16x32_bf16 v[22:25], v[142:145], v[182:185], v[22:25]
	v_mfma_f32_16x16x32_bf16 v[18:21], v[150:153], v[182:185], v[18:21]
	v_mfma_f32_16x16x32_bf16 v[6:9], v[142:145], v[190:193], v[6:9]
	v_mfma_f32_16x16x32_bf16 v[2:5], v[150:153], v[190:193], v[2:5]
	s_setprio 0
	s_barrier
	s_add_i32 s58, s58, 2
	s_add_u32 s52, s52, 0x100
	s_addc_u32 s53, s53, 0
	s_add_u32 s43, s43, 0x100
	s_addc_u32 s45, s45, 0
	s_cmp_gt_u32 s58, 13
	s_cbranch_scc0 .LBB0_510
	s_and_b64 vcc, exec, s[16:17]
	s_cbranch_vccz .LBB0_513
	s_barrier

; #define PG8_STAGE(bufoff, gbase, voff) do { _Pragma("unroll") for (int _i = 0; _i < 2; ++_i) \
;         __builtin_amdgcn_global_load_lds((const unsigned*)((const char*)(gbase) + (voff)[_i]), (PG8_LAS unsigned*)(lds + (bufoff) + ldsw + _i * 8192), 16, 0, 0); } while (0)
; #define PG8_LDA(dst, b, h) do { _Pragma("unroll") for (int m = 0; m < 4; ++m) _Pragma("unroll") for (int k = 0; k < 2; ++k) dst[m][k] = *(const PG8_LAS bf16x8*)(lds + PG8_SA(b, h) + aoff + m * 2048 + k * 1024); } while (0)
; #define PG8_LDB(dst, b, h) do { _Pragma("unroll") for (int n = 0; n < 2; ++n) _Pragma("unroll") for (int k = 0; k < 2; ++k) dst[n][k] = *(const PG8_LAS bf16x8*)(lds + PG8_SB(b, h) + boff + n * 2048 + k * 1024); } while (0)
; #define PG8_WAIT_V(n) asm volatile("s_waitcnt vmcnt(" #n ")" ::: "memory")
; #define PG8_WAIT_L(n) asm volatile("s_waitcnt lgkmcnt(" #n ")" ::: "memory")
; #define PG8_BAR __builtin_amdgcn_s_barrier()
; #define PG8_SCHED __builtin_amdgcn_sched_barrier(0)
; template <class Epi, class Sched, bool ALIGN_EPI = false, bool SP2 = false, bool SPLITK = false>
; __device__ __forceinline__ void gemm_phase(PG8_LAS unsigned char* lds, const Gemm g, const Sched& S, const Epi& E) {
;     ...
;         const char* nA = has_next ? (const char*)g.A + (size_t)nxt.pm * tstep : cA; const char* nB = has_next ? (const char*)g.Bt + (size_t)nxt.pn * tstep : cB;
;         for (int t = 0; t < nt; t += 2) {
;             const bool last = (t == nt - 2);
;             if constexpr (SPLITK) { if (t == nt1) E.mid(acc, cur, wr, wc, fr, fq); }
;             const char* a1 = PG8_TA(t + 1);
;             const char* a2 = last ? nA : PG8_TA(t + 2); const char* b2 = last ? nB : PG8_TB(t + 2);
;             const char* a3 = a2 + kstep; const char* b3 = b2 + kstep;
;             if (last && has_next) S.a_ready(nxt);
;             if constexpr (SP2) {
;             PG8_LDB(B0, 0, 0); PG8_LDB(B1, 0, 1); PG8_SCHED; PG8_LDA(At, 0, 0); PG8_STAGE(PG8_SA(1, 1), a1 + hstep, voffA);
;             PG8_WAIT_V(8); PG8_WAIT_L(0); PG8_BAR; PG8_MMA(0, 0, At, B0); PG8_MMA(0, 1, At, B1); PG8_BAR; PG8_SCHED;
;             PG8_LDA(At, 0, 1); PG8_STAGE(PG8_SB(0, 0), b2, voffB); PG8_STAGE(PG8_SB(0, 1), b2 + hstep, voffB); PG8_STAGE(PG8_SA(0, 0), a2, voffA);
;             PG8_WAIT_V(8); PG8_WAIT_L(0); PG8_BAR; PG8_MMA(1, 0, At, B0); PG8_MMA(1, 1, At, B1); PG8_BAR; PG8_SCHED;
.LBB0_701:
	s_add_u32 s40, s42, 0x100
	s_addc_u32 s41, s43, 0
	s_add_i32 s58, 0, 0x10000
	s_cmp_eq_u32 s57, 40
	s_cselect_b32 s49, s35, s41
	s_cselect_b32 s48, s34, s40
	s_cselect_b32 s47, s37, s45
	s_cselect_b32 s46, s36, s12
	s_add_i32 s59, 0, 0x14000
	v_add_u32_e32 v118, s58, v224
	v_add_u32_e32 v150, s59, v224
	ds_read_b128 v[82:85], v118
	ds_read_b128 v[94:97], v118 offset:1024
	ds_read_b128 v[106:109], v118 offset:2048
	ds_read_b128 v[118:121], v118 offset:3072
	ds_read_b128 v[130:133], v150
	ds_read_b128 v[142:145], v150 offset:1024
	ds_read_b128 v[146:149], v150 offset:2048
	ds_read_b128 v[150:153], v150 offset:3072
	s_add_i32 m0, s24, 0xc000
	ds_read_b128 v[162:165], v225
	ds_read_b128 v[166:169], v225 offset:1024
	ds_read_b128 v[170:173], v225 offset:2048
	ds_read_b128 v[174:177], v225 offset:3072
	ds_read_b128 v[178:181], v225 offset:4096
	ds_read_b128 v[182:185], v225 offset:5120
	ds_read_b128 v[186:189], v225 offset:6144
	ds_read_b128 v[190:193], v225 offset:7168
	global_load_lds_dwordx4 v200, s[42:43]
	s_add_i32 m0, s24, 0xe000
	s_nop 0
	global_load_lds_dwordx4 v202, s[42:43]
	s_waitcnt vmcnt(8)
	s_waitcnt lgkmcnt(0)
	s_barrier
	s_setprio 1
	s_waitcnt lgkmcnt(0)
	v_mfma_f32_16x16x32_bf16 v[158:161], v[82:85], v[162:165], v[158:161]
	v_mfma_f32_16x16x32_bf16 v[154:157], v[106:109], v[162:165], v[154:157]
	v_mfma_f32_16x16x32_bf16 v[126:129], v[82:85], v[170:173], v[126:129]
	v_mfma_f32_16x16x32_bf16 v[122:125], v[106:109], v[170:173], v[122:125]
	v_mfma_f32_16x16x32_bf16 v[102:105], v[82:85], v[178:181], v[102:105]
	v_mfma_f32_16x16x32_bf16 v[98:101], v[106:109], v[178:181], v[98:101]
	v_mfma_f32_16x16x32_bf16 v[78:81], v[82:85], v[186:189], v[78:81]
	v_mfma_f32_16x16x32_bf16 v[74:77], v[106:109], v[186:189], v[74:77]
	v_mfma_f32_16x16x32_bf16 v[158:161], v[94:97], v[166:169], v[158:161]
	v_mfma_f32_16x16x32_bf16 v[154:157], v[118:121], v[166:169], v[154:157]
	v_mfma_f32_16x16x32_bf16 v[126:129], v[94:97], v[174:177], v[126:129]
	v_mfma_f32_16x16x32_bf16 v[122:125], v[118:121], v[174:177], v[122:125]
	v_mfma_f32_16x16x32_bf16 v[102:105], v[94:97], v[182:185], v[102:105]
	v_mfma_f32_16x16x32_bf16 v[98:101], v[118:121], v[182:185], v[98:101]
	v_mfma_f32_16x16x32_bf16 v[78:81], v[94:97], v[190:193], v[78:81]
	v_mfma_f32_16x16x32_bf16 v[74:77], v[118:121], v[190:193], v[74:77]
	s_setprio 0
	s_setprio 1
	v_mfma_f32_16x16x32_bf16 v[138:141], v[130:133], v[162:165], v[138:141]
	v_mfma_f32_16x16x32_bf16 v[134:137], v[146:149], v[162:165], v[134:137]
	v_mfma_f32_16x16x32_bf16 v[114:117], v[130:133], v[170:173], v[114:117]
	v_mfma_f32_16x16x32_bf16 v[110:113], v[146:149], v[170:173], v[110:113]
	v_mfma_f32_16x16x32_bf16 v[90:93], v[130:133], v[178:181], v[90:93]
	v_mfma_f32_16x16x32_bf16 v[86:89], v[146:149], v[178:181], v[86:89]
	v_mfma_f32_16x16x32_bf16 v[70:73], v[130:133], v[186:189], v[70:73]
	v_mfma_f32_16x16x32_bf16 v[66:69], v[146:149], v[186:189], v[66:69]
	v_mfma_f32_16x16x32_bf16 v[138:141], v[142:145], v[166:169], v[138:141]
	v_mfma_f32_16x16x32_bf16 v[134:137], v[150:153], v[166:169], v[134:137]
	v_mfma_f32_16x16x32_bf16 v[114:117], v[142:145], v[174:177], v[114:117]
	v_mfma_f32_16x16x32_bf16 v[110:113], v[150:153], v[174:177], v[110:113]
	v_mfma_f32_16x16x32_bf16 v[90:93], v[142:145], v[182:185], v[90:93]
	v_mfma_f32_16x16x32_bf16 v[86:89], v[150:153], v[182:185], v[86:89]
	v_mfma_f32_16x16x32_bf16 v[70:73], v[142:145], v[190:193], v[70:73]
	v_mfma_f32_16x16x32_bf16 v[66:69], v[150:153], v[190:193], v[66:69]
	s_setprio 0
	s_barrier
	s_add_i32 s42, s58, s23
	s_mov_b32 m0, s42
	ds_read_b128 v[162:165], v225 offset:16384
	ds_read_b128 v[166:169], v225 offset:17408
	ds_read_b128 v[170:173], v225 offset:18432
	ds_read_b128 v[174:177], v225 offset:19456
	ds_read_b128 v[178:181], v225 offset:20480
	ds_read_b128 v[182:185], v225 offset:21504
	ds_read_b128 v[186:189], v225 offset:22528
	ds_read_b128 v[190:193], v225 offset:23552
	global_load_lds_dwordx4 v0, s[46:47]
	s_add_i32 m0, s42, 0x2000
	s_add_u32 s42, s46, 0xb0000
	s_addc_u32 s43, s47, 0
	s_add_i32 s58, s59, s23
	global_load_lds_dwordx4 v198, s[46:47]
	s_mov_b32 m0, s58
	s_nop 0
	global_load_lds_dwordx4 v0, s[42:43]
	s_add_i32 m0, s58, 0x2000
	s_nop 0
	global_load_lds_dwordx4 v198, s[42:43]
	s_mov_b32 m0, s24
	s_nop 0
	global_load_lds_dwordx4 v194, s[48:49]
	s_mov_b32 m0, s25
	s_nop 0
	global_load_lds_dwordx4 v196, s[48:49]
	s_waitcnt vmcnt(8)
	s_waitcnt lgkmcnt(0)
	s_barrier
	s_setprio 1
	s_waitcnt lgkmcnt(0)
	v_mfma_f32_16x16x32_bf16 v[62:65], v[82:85], v[162:165], v[62:65]
	v_mfma_f32_16x16x32_bf16 v[58:61], v[106:109], v[162:165], v[58:61]
	v_mfma_f32_16x16x32_bf16 v[46:49], v[82:85], v[170:173], v[46:49]
	v_mfma_f32_16x16x32_bf16 v[42:45], v[106:109], v[170:173], v[42:45]
	v_mfma_f32_16x16x32_bf16 v[30:33], v[82:85], v[178:181], v[30:33]
	v_mfma_f32_16x16x32_bf16 v[26:29], v[106:109], v[178:181], v[26:29]
	v_mfma_f32_16x16x32_bf16 v[14:17], v[82:85], v[186:189], v[14:17]
	v_mfma_f32_16x16x32_bf16 v[10:13], v[106:109], v[186:189], v[10:13]
	v_mfma_f32_16x16x32_bf16 v[62:65], v[94:97], v[166:169], v[62:65]
	v_mfma_f32_16x16x32_bf16 v[58:61], v[118:121], v[166:169], v[58:61]
	v_mfma_f32_16x16x32_bf16 v[46:49], v[94:97], v[174:177], v[46:49]
	v_mfma_f32_16x16x32_bf16 v[42:45], v[118:121], v[174:177], v[42:45]
	v_mfma_f32_16x16x32_bf16 v[30:33], v[94:97], v[182:185], v[30:33]
	v_mfma_f32_16x16x32_bf16 v[26:29], v[118:121], v[182:185], v[26:29]
	v_mfma_f32_16x16x32_bf16 v[14:17], v[94:97], v[190:193], v[14:17]
	v_mfma_f32_16x16x32_bf16 v[10:13], v[118:121], v[190:193], v[10:13]
	s_setprio 0
	s_setprio 1
	v_mfma_f32_16x16x32_bf16 v[54:57], v[130:133], v[162:165], v[54:57]
	v_mfma_f32_16x16x32_bf16 v[50:53], v[146:149], v[162:165], v[50:53]
	v_mfma_f32_16x16x32_bf16 v[38:41], v[130:133], v[170:173], v[38:41]
	v_mfma_f32_16x16x32_bf16 v[34:37], v[146:149], v[170:173], v[34:37]
	v_mfma_f32_16x16x32_bf16 v[22:25], v[130:133], v[178:181], v[22:25]
	v_mfma_f32_16x16x32_bf16 v[18:21], v[146:149], v[178:181], v[18:21]
	v_mfma_f32_16x16x32_bf16 v[6:9], v[130:133], v[186:189], v[6:9]
	v_mfma_f32_16x16x32_bf16 v[2:5], v[146:149], v[186:189], v[2:5]
	v_mfma_f32_16x16x32_bf16 v[54:57], v[142:145], v[166:169], v[54:57]
	v_mfma_f32_16x16x32_bf16 v[50:53], v[150:153], v[166:169], v[50:53]
	v_mfma_f32_16x16x32_bf16 v[38:41], v[142:145], v[174:177], v[38:41]
	v_mfma_f32_16x16x32_bf16 v[34:37], v[150:153], v[174:177], v[34:37]
	v_mfma_f32_16x16x32_bf16 v[22:25], v[142:145], v[182:185], v[22:25]
	v_mfma_f32_16x16x32_bf16 v[18:21], v[150:153], v[182:185], v[18:21]
	v_mfma_f32_16x16x32_bf16 v[6:9], v[142:145], v[190:193], v[6:9]
	v_mfma_f32_16x16x32_bf16 v[2:5], v[150:153], v[190:193], v[2:5]
	s_setprio 0
	s_barrier
; #define PG8_STAGE(bufoff, gbase, voff) do { _Pragma("unroll") for (int _i = 0; _i < 2; ++_i) \
;         __builtin_amdgcn_global_load_lds((const unsigned*)((const char*)(gbase) + (voff)[_i]), (PG8_LAS unsigned*)(lds + (bufoff) + ldsw + _i * 8192), 16, 0, 0); } while (0)
; #define PG8_LDA(dst, b, h) do { _Pragma("unroll") for (int m = 0; m < 4; ++m) _Pragma("unroll") for (int k = 0; k < 2; ++k) dst[m][k] = *(const PG8_LAS bf16x8*)(lds + PG8_SA(b, h) + aoff + m * 2048 + k * 1024); } while (0)
; #define PG8_LDB(dst, b, h) do { _Pragma("unroll") for (int n = 0; n < 2; ++n) _Pragma("unroll") for (int k = 0; k < 2; ++k) dst[n][k] = *(const PG8_LAS bf16x8*)(lds + PG8_SB(b, h) + boff + n * 2048 + k * 1024); } while (0)
; #define PG8_MMA(ai, bj, At, Bt) do { __builtin_amdgcn_s_setprio(1); _Pragma("unroll") for (int m = 0; m < 4; ++m) _Pragma("unroll") for (int n = 0; n < 2; ++n) _Pragma("unroll") for (int k = 0; k < 2; ++k) \
;         acc[ai][bj][m][n] = __builtin_amdgcn_mfma_f32_16x16x32_bf16(Bt[n][k], At[m][k], acc[ai][bj][m][n], 0, 0, 0); __builtin_amdgcn_s_setprio(0); } while (0)
; #define PG8_WAIT_V(n) asm volatile("s_waitcnt vmcnt(" #n ")" ::: "memory")
; #define PG8_WAIT_L(n) asm volatile("s_waitcnt lgkmcnt(" #n ")" ::: "memory")
; #define PG8_BAR __builtin_amdgcn_s_barrier()
; #define PG8_SCHED __builtin_amdgcn_sched_barrier(0)
; template <class Epi, class Sched, bool ALIGN_EPI = false, bool SP2 = false, bool SPLITK = false>
; __device__ __forceinline__ void gemm_phase(PG8_LAS unsigned char* lds, const Gemm g, const Sched& S, const Epi& E) {
;     ...
;             PG8_LDB(B0, 1, 0); PG8_LDB(B1, 1, 1); PG8_SCHED; PG8_LDA(At, 1, 0); PG8_STAGE(PG8_SA(0, 1), a2 + hstep, voffA);
;             PG8_WAIT_V(8); PG8_WAIT_L(0); PG8_BAR; PG8_MMA(0, 0, At, B0); PG8_MMA(0, 1, At, B1); PG8_BAR; PG8_SCHED;
;             PG8_LDA(At, 1, 1); PG8_STAGE(PG8_SB(1, 0), b3, voffB); PG8_STAGE(PG8_SB(1, 1), b3 + hstep, voffB); PG8_STAGE(PG8_SA(1, 0), a3, voffA);
;             PG8_WAIT_V(8); PG8_WAIT_L(0); PG8_BAR; PG8_MMA(1, 0, At, B0); PG8_MMA(1, 1, At, B1); PG8_BAR; PG8_SCHED;
	s_add_i32 s58, 0, 0x18000
	s_add_i32 s59, 0, 0x1c000
	v_add_u32_e32 v118, s58, v224
	v_add_u32_e32 v150, s59, v224
	ds_read_b128 v[82:85], v118
	ds_read_b128 v[94:97], v118 offset:1024
	ds_read_b128 v[106:109], v118 offset:2048
	ds_read_b128 v[118:121], v118 offset:3072
	ds_read_b128 v[130:133], v150
	ds_read_b128 v[142:145], v150 offset:1024
	ds_read_b128 v[146:149], v150 offset:2048
	ds_read_b128 v[150:153], v150 offset:3072
	s_add_u32 s42, s48, 0xb0000
	s_addc_u32 s43, s49, 0
	s_mov_b32 m0, s33
	ds_read_b128 v[162:165], v225 offset:32768
	ds_read_b128 v[166:169], v225 offset:33792
	ds_read_b128 v[170:173], v225 offset:34816
	ds_read_b128 v[174:177], v225 offset:35840
	ds_read_b128 v[178:181], v225 offset:36864
	ds_read_b128 v[182:185], v225 offset:37888
	ds_read_b128 v[186:189], v225 offset:38912
	ds_read_b128 v[190:193], v225 offset:39936
	global_load_lds_dwordx4 v194, s[42:43]
	s_mov_b32 m0, s50
	s_nop 0
	global_load_lds_dwordx4 v196, s[42:43]
	s_waitcnt vmcnt(8)
	s_waitcnt lgkmcnt(0)
	s_barrier
	s_setprio 1
	s_waitcnt lgkmcnt(0)
	v_mfma_f32_16x16x32_bf16 v[158:161], v[82:85], v[162:165], v[158:161]
	v_mfma_f32_16x16x32_bf16 v[154:157], v[106:109], v[162:165], v[154:157]
	v_mfma_f32_16x16x32_bf16 v[126:129], v[82:85], v[170:173], v[126:129]
	v_mfma_f32_16x16x32_bf16 v[122:125], v[106:109], v[170:173], v[122:125]
	v_mfma_f32_16x16x32_bf16 v[102:105], v[82:85], v[178:181], v[102:105]
	v_mfma_f32_16x16x32_bf16 v[98:101], v[106:109], v[178:181], v[98:101]
	v_mfma_f32_16x16x32_bf16 v[78:81], v[82:85], v[186:189], v[78:81]
	v_mfma_f32_16x16x32_bf16 v[74:77], v[106:109], v[186:189], v[74:77]
	v_mfma_f32_16x16x32_bf16 v[158:161], v[94:97], v[166:169], v[158:161]
	v_mfma_f32_16x16x32_bf16 v[154:157], v[118:121], v[166:169], v[154:157]
	v_mfma_f32_16x16x32_bf16 v[126:129], v[94:97], v[174:177], v[126:129]
	v_mfma_f32_16x16x32_bf16 v[122:125], v[118:121], v[174:177], v[122:125]
	v_mfma_f32_16x16x32_bf16 v[102:105], v[94:97], v[182:185], v[102:105]
	v_mfma_f32_16x16x32_bf16 v[98:101], v[118:121], v[182:185], v[98:101]
	v_mfma_f32_16x16x32_bf16 v[78:81], v[94:97], v[190:193], v[78:81]
	v_mfma_f32_16x16x32_bf16 v[74:77], v[118:121], v[190:193], v[74:77]
	s_setprio 0
	s_setprio 1
	v_mfma_f32_16x16x32_bf16 v[138:141], v[130:133], v[162:165], v[138:141]
	v_mfma_f32_16x16x32_bf16 v[134:137], v[146:149], v[162:165], v[134:137]
	v_mfma_f32_16x16x32_bf16 v[114:117], v[130:133], v[170:173], v[114:117]
	v_mfma_f32_16x16x32_bf16 v[110:113], v[146:149], v[170:173], v[110:113]
	v_mfma_f32_16x16x32_bf16 v[90:93], v[130:133], v[178:181], v[90:93]
	v_mfma_f32_16x16x32_bf16 v[86:89], v[146:149], v[178:181], v[86:89]
	v_mfma_f32_16x16x32_bf16 v[70:73], v[130:133], v[186:189], v[70:73]
	v_mfma_f32_16x16x32_bf16 v[66:69], v[146:149], v[186:189], v[66:69]
	v_mfma_f32_16x16x32_bf16 v[138:141], v[142:145], v[166:169], v[138:141]
	v_mfma_f32_16x16x32_bf16 v[134:137], v[150:153], v[166:169], v[134:137]
	v_mfma_f32_16x16x32_bf16 v[114:117], v[142:145], v[174:177], v[114:117]
	v_mfma_f32_16x16x32_bf16 v[110:113], v[150:153], v[174:177], v[110:113]
	v_mfma_f32_16x16x32_bf16 v[90:93], v[142:145], v[182:185], v[90:93]
	v_mfma_f32_16x16x32_bf16 v[86:89], v[150:153], v[182:185], v[86:89]
	v_mfma_f32_16x16x32_bf16 v[70:73], v[142:145], v[190:193], v[70:73]
	v_mfma_f32_16x16x32_bf16 v[66:69], v[150:153], v[190:193], v[66:69]
	s_setprio 0
	s_barrier
	s_add_i32 s42, s58, s23
	s_add_u32 vcc_lo, s46, 0x80
	s_addc_u32 vcc_hi, s47, 0
	s_mov_b32 m0, s42
	ds_read_b128 v[162:165], v225 offset:49152
	ds_read_b128 v[166:169], v225 offset:50176
	ds_read_b128 v[170:173], v225 offset:51200
	ds_read_b128 v[174:177], v225 offset:52224
	ds_read_b128 v[178:181], v225 offset:53248
	ds_read_b128 v[182:185], v225 offset:54272
	ds_read_b128 v[186:189], v225 offset:55296
	ds_read_b128 v[190:193], v225 offset:56320
	global_load_lds_dwordx4 v0, vcc
	s_add_i32 m0, s42, 0x2000
	s_add_u32 s42, s46, 0xb0080
	s_addc_u32 s43, s47, 0
	s_add_i32 s46, s59, s23
	global_load_lds_dwordx4 v198, vcc
	s_mov_b32 m0, s46
	s_nop 0
	global_load_lds_dwordx4 v0, s[42:43]
	s_add_i32 m0, s46, 0x2000
	s_nop 0
	global_load_lds_dwordx4 v198, s[42:43]
	s_add_u32 vcc_lo, s48, 0x80
	s_addc_u32 vcc_hi, s49, 0
	s_mov_b32 m0, s51
	s_nop 0
	global_load_lds_dwordx4 v194, vcc
	s_mov_b32 m0, s52
	s_nop 0
	global_load_lds_dwordx4 v196, vcc
	s_waitcnt vmcnt(8)
	s_waitcnt lgkmcnt(0)
	s_barrier
	s_setprio 1
	s_waitcnt lgkmcnt(0)
	v_mfma_f32_16x16x32_bf16 v[62:65], v[82:85], v[162:165], v[62:65]
	v_mfma_f32_16x16x32_bf16 v[58:61], v[106:109], v[162:165], v[58:61]
	v_mfma_f32_16x16x32_bf16 v[46:49], v[82:85], v[170:173], v[46:49]
	v_mfma_f32_16x16x32_bf16 v[42:45], v[106:109], v[170:173], v[42:45]
	v_mfma_f32_16x16x32_bf16 v[30:33], v[82:85], v[178:181], v[30:33]
	v_mfma_f32_16x16x32_bf16 v[26:29], v[106:109], v[178:181], v[26:29]
	v_mfma_f32_16x16x32_bf16 v[14:17], v[82:85], v[186:189], v[14:17]
	v_mfma_f32_16x16x32_bf16 v[10:13], v[106:109], v[186:189], v[10:13]
	v_mfma_f32_16x16x32_bf16 v[62:65], v[94:97], v[166:169], v[62:65]
	v_mfma_f32_16x16x32_bf16 v[58:61], v[118:121], v[166:169], v[58:61]
	v_mfma_f32_16x16x32_bf16 v[46:49], v[94:97], v[174:177], v[46:49]
	v_mfma_f32_16x16x32_bf16 v[42:45], v[118:121], v[174:177], v[42:45]
	v_mfma_f32_16x16x32_bf16 v[30:33], v[94:97], v[182:185], v[30:33]
	v_mfma_f32_16x16x32_bf16 v[26:29], v[118:121], v[182:185], v[26:29]
	v_mfma_f32_16x16x32_bf16 v[14:17], v[94:97], v[190:193], v[14:17]
	v_mfma_f32_16x16x32_bf16 v[10:13], v[118:121], v[190:193], v[10:13]
	s_setprio 0
	s_setprio 1
	v_mfma_f32_16x16x32_bf16 v[54:57], v[130:133], v[162:165], v[54:57]
	v_mfma_f32_16x16x32_bf16 v[50:53], v[146:149], v[162:165], v[50:53]
	v_mfma_f32_16x16x32_bf16 v[38:41], v[130:133], v[170:173], v[38:41]
	v_mfma_f32_16x16x32_bf16 v[34:37], v[146:149], v[170:173], v[34:37]
	v_mfma_f32_16x16x32_bf16 v[22:25], v[130:133], v[178:181], v[22:25]
	v_mfma_f32_16x16x32_bf16 v[18:21], v[146:149], v[178:181], v[18:21]
	v_mfma_f32_16x16x32_bf16 v[6:9], v[130:133], v[186:189], v[6:9]
	v_mfma_f32_16x16x32_bf16 v[2:5], v[146:149], v[186:189], v[2:5]
	v_mfma_f32_16x16x32_bf16 v[54:57], v[142:145], v[166:169], v[54:57]
	v_mfma_f32_16x16x32_bf16 v[50:53], v[150:153], v[166:169], v[50:53]
	v_mfma_f32_16x16x32_bf16 v[38:41], v[142:145], v[174:177], v[38:41]
	v_mfma_f32_16x16x32_bf16 v[34:37], v[150:153], v[174:177], v[34:37]
	v_mfma_f32_16x16x32_bf16 v[22:25], v[142:145], v[182:185], v[22:25]
	v_mfma_f32_16x16x32_bf16 v[18:21], v[150:153], v[182:185], v[18:21]
	v_mfma_f32_16x16x32_bf16 v[6:9], v[142:145], v[190:193], v[6:9]
	v_mfma_f32_16x16x32_bf16 v[2:5], v[150:153], v[190:193], v[2:5]
	s_setprio 0
	s_barrier
	s_add_i32 s57, s57, 2
	s_add_u32 s12, s12, 0x100
	s_addc_u32 s45, s45, 0
	s_cmp_gt_u32 s57, 41
	s_mov_b64 s[42:43], s[40:41]
	s_cbranch_scc0 .LBB0_701
	s_and_b64 vcc, exec, s[18:19]
	s_cbranch_vccz .LBB0_704
	s_barrier
